# attention phase: static s_setprio 1 for waves 4-7 (one wave per SIMD), reset at phase exit
# baseline (speedup 1.0000x reference)
.LBB0_2728:
	s_add_u32 s2, s4, s0
	s_addc_u32 s3, s5, s1
	global_load_dwordx4 v[4:7], v1, s[2:3]
	global_load_dwordx4 v[8:11], v1, s[2:3] offset:16
	s_add_u32 s2, s6, s0
	s_addc_u32 s3, s7, s1
	global_load_dwordx4 v[12:15], v1, s[2:3]
	global_load_dwordx4 v[16:19], v1, s[2:3] offset:16
	s_add_u32 s2, s8, s0
	s_addc_u32 s3, s9, s1
	global_load_dwordx4 v[20:23], v1, s[2:3]
	global_load_dwordx4 v[24:27], v1, s[2:3] offset:16
	s_add_u32 s2, s10, s0
	s_addc_u32 s3, s11, s1
	global_load_dwordx4 v[28:31], v1, s[2:3]
	global_load_dwordx4 v[32:35], v1, s[2:3] offset:16
	s_add_u32 s0, s0, 32
	s_addc_u32 s1, s1, 0
	s_cmpk_lg_i32 s0, 0x200
	s_waitcnt vmcnt(7)
	v_mov_b32_e32 v37, v4
	v_mov_b32_e32 v39, v6
	s_waitcnt vmcnt(6)
	v_mov_b32_e32 v41, v8
	s_waitcnt vmcnt(5)
	v_mov_b32_e32 v45, v12
	v_mov_b32_e32 v47, v14
	s_waitcnt vmcnt(4)
	v_mov_b32_e32 v49, v16
	s_waitcnt vmcnt(3)
	v_mov_b32_e32 v36, v20
	v_mov_b32_e32 v4, v21
	v_mov_b32_e32 v38, v22
	s_waitcnt vmcnt(1)
	v_mov_b32_e32 v44, v28
	v_mov_b32_e32 v12, v29
	v_pk_fma_f32 v[2:3], v[36:37], v[44:45], v[2:3]
	v_mov_b32_e32 v46, v30
	v_pk_fma_f32 v[2:3], v[4:5], v[12:13], v[2:3]
	v_mov_b32_e32 v6, v23
	v_mov_b32_e32 v14, v31
	v_pk_fma_f32 v[2:3], v[38:39], v[46:47], v[2:3]
	v_mov_b32_e32 v40, v24
	s_waitcnt vmcnt(0)
	v_mov_b32_e32 v48, v32
	v_pk_fma_f32 v[2:3], v[6:7], v[14:15], v[2:3]
	v_mov_b32_e32 v8, v25
	v_mov_b32_e32 v16, v33
	v_pk_fma_f32 v[2:3], v[40:41], v[48:49], v[2:3]
	v_mov_b32_e32 v43, v10
	v_mov_b32_e32 v51, v18
	v_mov_b32_e32 v42, v26
	v_mov_b32_e32 v50, v34
	v_pk_fma_f32 v[2:3], v[8:9], v[16:17], v[2:3]
	v_mov_b32_e32 v10, v27
	v_mov_b32_e32 v18, v35
	v_pk_fma_f32 v[2:3], v[42:43], v[50:51], v[2:3]
	s_nop 0
	v_pk_fma_f32 v[2:3], v[10:11], v[18:19], v[2:3]
	s_cbranch_scc1 .LBB0_2728
	s_add_u32 s0, s92, 0x30d00000
	v_writelane_b32 v255, s0, 20
	s_addc_u32 s0, s93, 0
	v_writelane_b32 v255, s0, 6
	s_getreg_b32 s0, hwreg(HW_REG_XCC_ID, 0, 4)
	s_and_b32 s0, s0, 15
	s_add_u32 s2, s92, 0x34e00000
	s_addc_u32 s3, s93, 0
	v_writelane_b32 v254, s2, 3
	v_writelane_b32 v255, s0, 10
	s_add_u32 s55, s92, 0x38f00000
	v_writelane_b32 v254, s3, 4
	v_writelane_b32 v255, s92, 21
	v_readlane_b32 s7, v254, 0
	s_addc_u32 s95, s93, 0
	s_lshr_b32 s2, s7, 7
	s_bfe_u32 s3, s7, 0x10006
	s_lshl_b32 s46, s2, 5
	s_cmpk_lt_u32 s7, 0x100
	s_cbranch_scc1 .Lat_prio_skip
	s_setprio 1
.Lat_prio_skip:
	s_cmpk_lt_u32 s7, 0x200
	v_readlane_b32 s8, v254, 28
	s_cselect_b64 s[56:57], -1, 0
	s_lshl_b32 s5, s8, 5
	v_writelane_b32 v255, s93, 22
	s_and_b32 s5, s5, 0x7fffff80
	v_mul_f32_e32 v1, 0x3fb8aa3b, v3
	v_mul_f32_e32 v2, 0x3fb8aa3b, v2
	s_lshl_b32 s4, s8, 2
	v_writelane_b32 v255, s5, 11
	s_lshl_b32 s5, s8, 4
	v_exp_f32_e32 v1, v1
	v_exp_f32_e32 v2, v2
	s_and_b32 s80, s5, 48
	s_or_b32 s5, s4, 1
	s_lshl_b32 s81, s8, 12
	s_lshl_b32 s6, s5, 2
	s_lshl_b32 s83, s5, 10
	s_or_b32 s5, s4, 2
	s_or_b32 s4, s4, 3
	s_lshl_b32 s85, s3, 7
	s_and_b32 s82, s6, 52
	s_lshl_b32 s6, s5, 2
	s_lshl_b32 s87, s5, 10
	s_lshl_b32 s5, s4, 2
	s_add_i32 s97, s81, 0
	s_lshl_b32 s3, s3, 14
	s_and_b32 s86, s6, 56
	s_and_b32 s90, s5, 60
	s_lshl_b32 s91, s4, 10
	s_lshl_b32 s96, s8, 3
	s_add_i32 s42, s97, 0x10000
	s_add_i32 s43, s3, 0
	v_sub_f32_e32 v1, v1, v2
	s_bitcmp1_b32 s7, 6
	v_add_f32_e32 v1, 0x3eb60549, v1
	s_cselect_b64 s[6:7], -1, 0
	s_lshl_b32 s2, s2, 15
	s_add_i32 s92, 0, 0x26c40
	v_mbcnt_lo_u32_b32 v2, -1, 0
	s_mov_b32 s45, 0
	v_cmp_eq_u32_e64 s[0:1], 0, v0
	v_cndmask_b32_e64 v1, 1.0, v1, s[6:7]
	s_add_i32 s33, s2, 0
	s_sub_i32 s47, 0, s46
	s_add_i32 s54, s96, 64
	v_mov_b32_e32 v3, 0
	s_movk_i32 s93, 0xff00
	v_cndmask_b32_e64 v243, 0, 1, s[56:57]
	s_mov_b64 s[58:59], 0x80
	s_mov_b64 s[52:53], 0x100
	s_mov_b64 s[48:49], 0x180
	s_movk_i32 s88, 0x80
	s_movk_i32 s89, 0xfee0
	s_mov_b32 s94, 0x3b800000
	s_mov_b32 s84, 0x800000
	v_mov_b32_e32 v245, s92
	v_lshrrev_b32_e32 v4, 5, v242
	v_lshlrev_b32_e32 v4, 4, v4
	v_lshlrev_b32_e32 v5, 4, v242
	v_and_b32_e32 v5, 0x70, v5
	v_xor_b32_e32 v4, v4, v5
	v_and_b32_e32 v5, 31, v242
	v_lshl_or_b32 v246, v5, 8, v4
	v_mov_b32_e32 v247, 0xdf
	v_mov_b32_e32 v248, 0xf149f2ca
	v_mbcnt_hi_u32_b32 v249, -1, v2
	v_mov_b32_e32 v244, 0x3727c5ac
	s_mov_b32 s3, 0
	s_mov_b32 s32, 0x20800
	v_lshrrev_b32_e32 v4, 4, v242
	v_and_b32_e32 v5, 15, v242
	v_xor_b32_e32 v5, v5, v4
	v_lshlrev_b32_e32 v5, 4, v5
	v_lshl_add_u32 v4, v4, 12, v5
	v_xor_b32_e32 v5, 64, v4
	v_add_u32_e32 v5, 0x4000, v5
	v_add_u32_e32 v6, 0x8000, v4
	v_add_u32_e32 v7, 0x8000, v5
	v_bfe_u32 v8, v242, 2, 3
	v_and_b32_e32 v9, 3, v242
	v_lshlrev_b32_e32 v9, 4, v9
	v_lshl_add_u32 v8, v8, 12, v9
	v_and_b32_e32 v9, 32, v242
	v_lshl_add_u32 v8, v9, 1, v8
	v_add_u32_e32 v9, 0x80, v8
	v_add_u32_e32 v10, 0x100, v8
	v_add_u32_e32 v11, 0x180, v8
	v_lshl_add_u32 v12, v242, 5, s32
	ds_write_b128 v12, v[4:7]
	ds_write_b128 v12, v[8:11] offset:16
	s_waitcnt lgkmcnt(0)
	s_branch .LBB0_2731

.LBB0_3039:
	s_setprio 0
	v_readlane_b32 s92, v255, 21
	v_readlane_b32 s88, v254, 48
	v_readlane_b32 s84, v255, 15
	v_readlane_b32 s94, v255, 19
	v_readlane_b32 s93, v255, 22
	v_readlane_b32 s86, v255, 13
	v_readlane_b32 s89, v254, 49
	v_readlane_b32 s85, v255, 16
	v_readlane_b32 s87, v255, 14
